# key-norm table as (max,count) pairs read with one 8-byte load per lane issued with the pre-pass loads
# baseline (speedup 1.0000x reference)
.LBB0_543:
	s_and_b64 vcc, exec, s[38:39]
	s_nop 0
	s_nop 0
	s_load_dwordx2 s[34:35], s[0:1], 32
	s_waitcnt lgkmcnt(0)
	s_load_dwordx2 s[28:29], s[0:1], 40
	s_waitcnt lgkmcnt(0)
	s_load_dwordx2 s[30:31], s[0:1], 48
	s_waitcnt lgkmcnt(0)
	s_load_dwordx2 s[22:23], s[0:1], 56
	s_waitcnt lgkmcnt(0)
	s_nop 0
	s_nop 0
	s_nop 0
	s_nop 0
	s_nop 0
	s_load_dwordx2 s[10:11], s[0:1], 0x60
	s_waitcnt lgkmcnt(0)
	s_load_dwordx2 s[26:27], s[0:1], 0x68
	s_waitcnt lgkmcnt(0)
	s_cbranch_vccnz .LBB0_554
	v_readlane_b32 s100, v252, 9
	s_nop 3
	s_lshr_b32 s101, s100, 3
	s_and_b32 s100, s100, 7
	s_lshr_b32 s2, s101, 3
	s_and_b32 s3, s101, 7
	s_lshl_b32 s2, s2, 12
	s_lshl_b32 s20, s100, 9
	s_add_i32 s2, s2, s20
	s_mul_i32 s20, s2, 0x1e00
	s_lshl_b32 s3, s3, 7
	s_add_u32 s20, s20, s3
	s_add_u32 s20, s20, 0x7001200
	s_add_u32 s2, s26, s20
	s_addc_u32 s3, s27, 0
	v_lshrrev_b32_e32 v32, 3, v184
	v_mul_u32_u24_e32 v32, 0x1e00, v32
	v_and_b32_e32 v33, 7, v184
	v_lshl_add_u32 v32, v33, 4, v32
	global_load_dwordx4 v[36:39], v32, s[2:3]
	v_add_u32_e32 v33, 0x78000, v32
	global_load_dwordx4 v[40:43], v33, s[2:3]
	v_add_u32_e32 v33, 0xf0000, v32
	global_load_dwordx4 v[44:47], v33, s[2:3]
	v_add_u32_e32 v33, 0x168000, v32
	global_load_dwordx4 v[48:51], v33, s[2:3]
	v_add_u32_e32 v33, 0x1e0000, v32
	global_load_dwordx4 v[52:55], v33, s[2:3]
	v_add_u32_e32 v33, 0x258000, v32
	global_load_dwordx4 v[56:59], v33, s[2:3]
	v_add_u32_e32 v33, 0x2d0000, v32
	global_load_dwordx4 v[60:63], v33, s[2:3]
	v_add_u32_e32 v33, 0x348000, v32
	global_load_dwordx4 v[64:67], v33, s[2:3]
	v_mov_b32_e32 v70, 0
	s_waitcnt vmcnt(7)
	v_lshlrev_b32_e32 v72, 16, v36
	v_and_b32_e32 v73, 0xffff0000, v36
	v_mul_f32_e32 v71, v72, v72
	v_fmac_f32_e32 v71, v73, v73
	v_lshlrev_b32_e32 v72, 16, v37
	v_and_b32_e32 v73, 0xffff0000, v37
	v_fmac_f32_e32 v71, v72, v72
	v_fmac_f32_e32 v71, v73, v73
	v_lshlrev_b32_e32 v72, 16, v38
	v_and_b32_e32 v73, 0xffff0000, v38
	v_fmac_f32_e32 v71, v72, v72
	v_fmac_f32_e32 v71, v73, v73
	v_lshlrev_b32_e32 v72, 16, v39
	v_and_b32_e32 v73, 0xffff0000, v39
	v_fmac_f32_e32 v71, v72, v72
	v_fmac_f32_e32 v71, v73, v73
	v_max_f32_e32 v70, v70, v71
	s_waitcnt vmcnt(6)
	v_lshlrev_b32_e32 v72, 16, v40
	v_and_b32_e32 v73, 0xffff0000, v40
	v_mul_f32_e32 v71, v72, v72
	v_fmac_f32_e32 v71, v73, v73
	v_lshlrev_b32_e32 v72, 16, v41
	v_and_b32_e32 v73, 0xffff0000, v41
	v_fmac_f32_e32 v71, v72, v72
	v_fmac_f32_e32 v71, v73, v73
	v_lshlrev_b32_e32 v72, 16, v42
	v_and_b32_e32 v73, 0xffff0000, v42
	v_fmac_f32_e32 v71, v72, v72
	v_fmac_f32_e32 v71, v73, v73
	v_lshlrev_b32_e32 v72, 16, v43
	v_and_b32_e32 v73, 0xffff0000, v43
	v_fmac_f32_e32 v71, v72, v72
	v_fmac_f32_e32 v71, v73, v73
	v_max_f32_e32 v70, v70, v71
	s_waitcnt vmcnt(5)
	v_lshlrev_b32_e32 v72, 16, v44
	v_and_b32_e32 v73, 0xffff0000, v44
	v_mul_f32_e32 v71, v72, v72
	v_fmac_f32_e32 v71, v73, v73
	v_lshlrev_b32_e32 v72, 16, v45
	v_and_b32_e32 v73, 0xffff0000, v45
	v_fmac_f32_e32 v71, v72, v72
	v_fmac_f32_e32 v71, v73, v73
	v_lshlrev_b32_e32 v72, 16, v46
	v_and_b32_e32 v73, 0xffff0000, v46
	v_fmac_f32_e32 v71, v72, v72
	v_fmac_f32_e32 v71, v73, v73
	v_lshlrev_b32_e32 v72, 16, v47
	v_and_b32_e32 v73, 0xffff0000, v47
	v_fmac_f32_e32 v71, v72, v72
	v_fmac_f32_e32 v71, v73, v73
	v_max_f32_e32 v70, v70, v71
	s_waitcnt vmcnt(4)
	v_lshlrev_b32_e32 v72, 16, v48
	v_and_b32_e32 v73, 0xffff0000, v48
	v_mul_f32_e32 v71, v72, v72
	v_fmac_f32_e32 v71, v73, v73
	v_lshlrev_b32_e32 v72, 16, v49
	v_and_b32_e32 v73, 0xffff0000, v49
	v_fmac_f32_e32 v71, v72, v72
	v_fmac_f32_e32 v71, v73, v73
	v_lshlrev_b32_e32 v72, 16, v50
	v_and_b32_e32 v73, 0xffff0000, v50
	v_fmac_f32_e32 v71, v72, v72
	v_fmac_f32_e32 v71, v73, v73
	v_lshlrev_b32_e32 v72, 16, v51
	v_and_b32_e32 v73, 0xffff0000, v51
	v_fmac_f32_e32 v71, v72, v72
	v_fmac_f32_e32 v71, v73, v73
	v_max_f32_e32 v70, v70, v71
	s_waitcnt vmcnt(3)
	v_lshlrev_b32_e32 v72, 16, v52
	v_and_b32_e32 v73, 0xffff0000, v52
	v_mul_f32_e32 v71, v72, v72
	v_fmac_f32_e32 v71, v73, v73
	v_lshlrev_b32_e32 v72, 16, v53
	v_and_b32_e32 v73, 0xffff0000, v53
	v_fmac_f32_e32 v71, v72, v72
	v_fmac_f32_e32 v71, v73, v73
	v_lshlrev_b32_e32 v72, 16, v54
	v_and_b32_e32 v73, 0xffff0000, v54
	v_fmac_f32_e32 v71, v72, v72
	v_fmac_f32_e32 v71, v73, v73
	v_lshlrev_b32_e32 v72, 16, v55
	v_and_b32_e32 v73, 0xffff0000, v55
	v_fmac_f32_e32 v71, v72, v72
	v_fmac_f32_e32 v71, v73, v73
	v_max_f32_e32 v70, v70, v71
	s_waitcnt vmcnt(2)
	v_lshlrev_b32_e32 v72, 16, v56
	v_and_b32_e32 v73, 0xffff0000, v56
	v_mul_f32_e32 v71, v72, v72
	v_fmac_f32_e32 v71, v73, v73
	v_lshlrev_b32_e32 v72, 16, v57
	v_and_b32_e32 v73, 0xffff0000, v57
	v_fmac_f32_e32 v71, v72, v72
	v_fmac_f32_e32 v71, v73, v73
	v_lshlrev_b32_e32 v72, 16, v58
	v_and_b32_e32 v73, 0xffff0000, v58
	v_fmac_f32_e32 v71, v72, v72
	v_fmac_f32_e32 v71, v73, v73
	v_lshlrev_b32_e32 v72, 16, v59
	v_and_b32_e32 v73, 0xffff0000, v59
	v_fmac_f32_e32 v71, v72, v72
	v_fmac_f32_e32 v71, v73, v73
	v_max_f32_e32 v70, v70, v71
	s_waitcnt vmcnt(1)
	v_lshlrev_b32_e32 v72, 16, v60
	v_and_b32_e32 v73, 0xffff0000, v60
	v_mul_f32_e32 v71, v72, v72
	v_fmac_f32_e32 v71, v73, v73
	v_lshlrev_b32_e32 v72, 16, v61
	v_and_b32_e32 v73, 0xffff0000, v61
	v_fmac_f32_e32 v71, v72, v72
	v_fmac_f32_e32 v71, v73, v73
	v_lshlrev_b32_e32 v72, 16, v62
	v_and_b32_e32 v73, 0xffff0000, v62
	v_fmac_f32_e32 v71, v72, v72
	v_fmac_f32_e32 v71, v73, v73
	v_lshlrev_b32_e32 v72, 16, v63
	v_and_b32_e32 v73, 0xffff0000, v63
	v_fmac_f32_e32 v71, v72, v72
	v_fmac_f32_e32 v71, v73, v73
	v_max_f32_e32 v70, v70, v71
	s_waitcnt vmcnt(0)
	v_lshlrev_b32_e32 v72, 16, v64
	v_and_b32_e32 v73, 0xffff0000, v64
	v_mul_f32_e32 v71, v72, v72
	v_fmac_f32_e32 v71, v73, v73
	v_lshlrev_b32_e32 v72, 16, v65
	v_and_b32_e32 v73, 0xffff0000, v65
	v_fmac_f32_e32 v71, v72, v72
	v_fmac_f32_e32 v71, v73, v73
	v_lshlrev_b32_e32 v72, 16, v66
	v_and_b32_e32 v73, 0xffff0000, v66
	v_fmac_f32_e32 v71, v72, v72
	v_fmac_f32_e32 v71, v73, v73
	v_lshlrev_b32_e32 v72, 16, v67
	v_and_b32_e32 v73, 0xffff0000, v67
	v_fmac_f32_e32 v71, v72, v72
	v_fmac_f32_e32 v71, v73, v73
	v_max_f32_e32 v70, v70, v71
	v_and_b32_e32 v74, 63, v184
	v_lshlrev_b32_e32 v74, 2, v74
	v_xor_b32_e32 v75, 32, v74
	ds_bpermute_b32 v72, v75, v70
	s_waitcnt lgkmcnt(0)
	v_max_f32_e32 v70, v70, v72
	v_xor_b32_e32 v75, 64, v74
	ds_bpermute_b32 v72, v75, v70
	s_waitcnt lgkmcnt(0)
	v_max_f32_e32 v70, v70, v72
	v_xor_b32_e32 v75, 128, v74
	ds_bpermute_b32 v72, v75, v70
	s_waitcnt lgkmcnt(0)
	v_max_f32_e32 v70, v70, v72
	s_lshl_b32 s2, s101, 6
	s_lshl_b32 s3, s16, 11
	s_add_i32 s2, s2, s3
	s_getpc_b64 s[100:101]
	s_add_u32 s100, s100, g_ctl@rel32@lo+51204
	s_addc_u32 s101, s101, g_ctl@rel32@hi+51212
	s_add_u32 s100, s100, s2
	s_addc_u32 s101, s101, 0
	v_lshlrev_b32_e32 v74, 1, v74
	s_mov_b64 exec, 0xff
	global_atomic_umax v72, v74, v70, s[100:101] sc0
	s_waitcnt vmcnt(0)
	global_atomic_add v74, v193, s[100:101] offset:4
	s_mov_b64 exec, -1
	s_add_u32 s24, s26, 0x4000000
	s_addc_u32 s25, s27, 0
	v_readlane_b32 s2, v252, 24
	s_add_u32 s26, s26, 0x7000000
	v_readlane_b32 s3, v252, 25
	s_addc_u32 s27, s27, 0
	s_lshl_b64 s[10:11], s[2:3], 2
	s_add_u32 s18, s34, s10
	s_addc_u32 s19, s35, s11
	s_add_u32 s28, s28, s10
	s_addc_u32 s29, s29, s11
	s_lshl_b32 s10, s16, 2
	s_add_u32 s30, s30, 16
	v_readlane_b32 s2, v252, 9
	s_addc_u32 s31, s31, 0
	s_lshl_b32 s11, s16, 9
	s_mov_b32 s12, s2
	s_mov_b32 s13, s2
	v_readlane_b32 s3, v252, 10
	s_branch .LBB0_546

.LBB0_574:
	s_sub_u32 s2, s26, s10
	s_lshr_b32 s2, s2, 14
	s_lshl_b32 s2, s2, 6
	s_lshl_b32 s3, s16, 11
	s_add_i32 s2, s2, s3
	s_getpc_b64 s[100:101]
	s_add_u32 s100, s100, g_ctl@rel32@lo+51204
	s_addc_u32 s101, s101, g_ctl@rel32@hi+51212
	s_add_u32 s100, s100, s2
	s_addc_u32 s101, s101, 0
	v_readfirstlane_b32 s2, v165
	s_nop 3
	s_lshr_b32 s2, s2, 6
	s_lshl_b32 s2, s2, 5
	s_lshl_b32 s3, s48, 8
	s_add_i32 s2, s2, s3
	s_add_i32 s20, s2, -32
	s_lshl_b32 s42, s20, 2
	s_mul_i32 s20, s20, 0x1e00
	s_add_u32 s20, s20, 0x7001200
	s_add_u32 s2, s28, s20
	s_addc_u32 s3, s29, 0
	v_and_b32_e32 v60, 31, v165
	v_mul_u32_u24_e32 v60, 0x1e00, v60
	v_bfe_u32 v61, v165, 5, 1
	v_lshl_add_u32 v60, v61, 4, v60
	v_add_u32_e32 v61, s42, v179
	global_load_dwordx4 v[64:67], v60, s[2:3] offset:0
	global_load_dwordx4 v[68:71], v60, s[2:3] offset:32
	global_load_dwordx4 v[72:75], v60, s[2:3] offset:64
	global_load_dwordx4 v[76:79], v60, s[2:3] offset:96
	v_and_b32_e32 v215, 7, v165
	v_lshlrev_b32_e32 v215, 3, v215
	global_load_dwordx2 v[210:211], v215, s[100:101] sc1
	ds_read_b128 v[32:35], v61
	ds_read_b128 v[36:39], v61 offset:32
	ds_read_b128 v[40:43], v61 offset:64
	ds_read_b128 v[44:47], v61 offset:96
	s_waitcnt lgkmcnt(0)
	s_waitcnt vmcnt(4)
	v_mfma_f32_32x32x16_bf16 v[32:47], v[64:67], v[96:99], v[32:47]
	s_waitcnt vmcnt(3)
	v_mfma_f32_32x32x16_bf16 v[32:47], v[68:71], v[100:103], v[32:47]
	s_waitcnt vmcnt(2)
	v_mfma_f32_32x32x16_bf16 v[32:47], v[72:75], v[104:107], v[32:47]
	s_waitcnt vmcnt(1)
	v_mfma_f32_32x32x16_bf16 v[32:47], v[76:79], v[108:111], v[32:47]
	s_nop 11
	v_max3_f32 v222, v32, v33, v34
	v_max3_f32 v222, v222, v35, v36
	v_max3_f32 v222, v222, v37, v38
	v_max3_f32 v222, v222, v39, v40
	v_max3_f32 v222, v222, v41, v42
	v_max3_f32 v222, v222, v43, v44
	v_max3_f32 v222, v222, v45, v46
	v_max_f32_e32 v222, v222, v47
	ds_bpermute_b32 v183, v180, v222
	s_waitcnt lgkmcnt(0)
	v_max_f32_e32 v183, v183, v183
	v_max_f32_e32 v182, v222, v183
	v_sub_f32_e32 v182, v182, v161
	v_add_f32_e32 v255, 0xc2200000, v182
	s_waitcnt vmcnt(0)
	s_mov_b32 s20, 0
.Lfox_km_chk:
	v_cmp_gt_u32_e32 vcc, 64, v211
	s_cbranch_vccz .Lfox_km_ready
	s_sleep 2
	global_load_dwordx2 v[210:211], v215, s[100:101] sc1
	s_waitcnt vmcnt(0)
	s_add_i32 s20, s20, 1
	s_cmp_lt_u32 s20, 0x20000
	s_cbranch_scc1 .Lfox_km_chk
	v_mov_b32_e32 v254, 0x7f800000
	s_branch .Lfox_kpass_done
.Lfox_km_ready:
	v_and_b32_e32 v214, 63, v165
	v_lshlrev_b32_e32 v214, 2, v214
	v_xor_b32_e32 v217, 4, v214
	ds_bpermute_b32 v216, v217, v210
	s_waitcnt lgkmcnt(0)
	v_add_f32_e32 v210, v210, v216
	v_xor_b32_e32 v217, 8, v214
	ds_bpermute_b32 v216, v217, v210
	s_waitcnt lgkmcnt(0)
	v_add_f32_e32 v210, v210, v216
	v_xor_b32_e32 v217, 16, v214
	ds_bpermute_b32 v216, v217, v210
	s_waitcnt lgkmcnt(0)
	v_add_f32_e32 v210, v210, v216
	v_mov_b32_e32 v254, v210
	s_branch .Lfox_kpass_done
	s_mov_b64 s[2:3], 0x7001200
	v_lshl_add_u64 v[202:203], v[158:159], 0, s[2:3]
	s_mov_b64 s[2:3], 0x78000
	v_lshl_add_u64 v[204:205], v[202:203], 0, s[2:3]
	v_mov_b32_e32 v210, 0
	s_lshl_b32 s20, s48, 1
	s_add_i32 s100, s20, 1
	s_add_i32 s20, s48, 1
	s_lshr_b32 s20, s20, 1
	s_mov_b32 s101, 0
	s_mov_b32 s3, 0
	s_min_u32 s2, s101, s100
	s_mul_i32 s2, s2, 0xf0000
	s_add_i32 s101, s101, 1
	v_lshl_add_u64 v[206:207], v[202:203], 0, s[2:3]
	v_lshl_add_u64 v[208:209], v[204:205], 0, s[2:3]
	global_load_dwordx4 v[32:35], v[206:207], off
	global_load_dwordx4 v[36:39], v[208:209], off
	s_min_u32 s2, s101, s100
	s_mul_i32 s2, s2, 0xf0000
	s_add_i32 s101, s101, 1
	v_lshl_add_u64 v[206:207], v[202:203], 0, s[2:3]
	v_lshl_add_u64 v[208:209], v[204:205], 0, s[2:3]
	global_load_dwordx4 v[40:43], v[206:207], off
	global_load_dwordx4 v[44:47], v[208:209], off
	s_min_u32 s2, s101, s100
	s_mul_i32 s2, s2, 0xf0000
	s_add_i32 s101, s101, 1
	v_lshl_add_u64 v[206:207], v[202:203], 0, s[2:3]
	v_lshl_add_u64 v[208:209], v[204:205], 0, s[2:3]
	global_load_dwordx4 v[48:51], v[206:207], off
	global_load_dwordx4 v[52:55], v[208:209], off
	s_min_u32 s2, s101, s100
	s_mul_i32 s2, s2, 0xf0000
	s_add_i32 s101, s101, 1
	v_lshl_add_u64 v[206:207], v[202:203], 0, s[2:3]
	v_lshl_add_u64 v[208:209], v[204:205], 0, s[2:3]
	global_load_dwordx4 v[56:59], v[206:207], off
	global_load_dwordx4 v[60:63], v[208:209], off
	s_min_u32 s2, s101, s100
	s_mul_i32 s2, s2, 0xf0000
	s_add_i32 s101, s101, 1
	v_lshl_add_u64 v[206:207], v[202:203], 0, s[2:3]
	v_lshl_add_u64 v[208:209], v[204:205], 0, s[2:3]
	global_load_dwordx4 v[64:67], v[206:207], off
	global_load_dwordx4 v[68:71], v[208:209], off
	s_min_u32 s2, s101, s100
	s_mul_i32 s2, s2, 0xf0000
	s_add_i32 s101, s101, 1
	v_lshl_add_u64 v[206:207], v[202:203], 0, s[2:3]
	v_lshl_add_u64 v[208:209], v[204:205], 0, s[2:3]
	global_load_dwordx4 v[72:75], v[206:207], off
	global_load_dwordx4 v[76:79], v[208:209], off
	s_min_u32 s2, s101, s100
	s_mul_i32 s2, s2, 0xf0000
	s_add_i32 s101, s101, 1
	v_lshl_add_u64 v[206:207], v[202:203], 0, s[2:3]
	v_lshl_add_u64 v[208:209], v[204:205], 0, s[2:3]
	global_load_dwordx4 v[80:83], v[206:207], off
	global_load_dwordx4 v[84:87], v[208:209], off
	s_min_u32 s2, s101, s100
	s_mul_i32 s2, s2, 0xf0000
	s_add_i32 s101, s101, 1
	v_lshl_add_u64 v[206:207], v[202:203], 0, s[2:3]
	v_lshl_add_u64 v[208:209], v[204:205], 0, s[2:3]
	global_load_dwordx4 v[88:91], v[206:207], off
	global_load_dwordx4 v[92:95], v[208:209], off
